# C/B loops: PV MFMAs interleaved into the exp block with early V fragment reads
# baseline (speedup 1.0000x reference)
; #define FLAS __attribute__((address_space(3)))
; #define FA_SB() __builtin_amdgcn_sched_barrier(0)
; __device__ __forceinline__ unsigned cvtpk(float lo, float hi) { f32x2_t v = {lo, hi}; bf16x2_t b = __builtin_convertvector(v, bf16x2_t); return __builtin_bit_cast(unsigned, b); }
; template <int MODE> __device__ __forceinline__ void attn_unit(FLAS unsigned char* lds, const Unit u) {
;     ...
;             float ps = 0.f;
; #pragma unroll
;             for (int r = 0; r < 16; ++r) { p0[r] = __builtin_amdgcn_exp2f(p0[r]); p1[r] = __builtin_amdgcn_exp2f(p1[r]); ps += p0[r] + p1[r]; }
;             lsum += ps;
;             u32x4 pw[4];
;             pw[0] = (u32x4){cvtpk(p0[0], p0[1]), cvtpk(p0[2], p0[3]), cvtpk(p0[4], p0[5]), cvtpk(p0[6], p0[7])};
;             pw[1] = (u32x4){cvtpk(p0[8], p0[9]), cvtpk(p0[10], p0[11]), cvtpk(p0[12], p0[13]), cvtpk(p0[14], p0[15])};
;             pw[2] = (u32x4){cvtpk(p1[0], p1[1]), cvtpk(p1[2], p1[3]), cvtpk(p1[4], p1[5]), cvtpk(p1[6], p1[7])};
;             pw[3] = (u32x4){cvtpk(p1[8], p1[9]), cvtpk(p1[10], p1[11]), cvtpk(p1[12], p1[13]), cvtpk(p1[14], p1[15])};
;             FA_SB();
; #pragma unroll
;             for (int s = 0; s < 4; ++s) {
;                 if (s < 3) {
; #pragma unroll
;                     for (int db = 0; db < NDB; ++db) vf[(s + 1) & 1][db] = *(const FLAS u32x4*)(vb + db * 32 * VPITCH + (s + 1) * 32); }
; #pragma unroll
;                 for (int db = 0; db < NDB; ++db) o[db] = __builtin_amdgcn_mfma_f32_32x32x16_bf16(__builtin_bit_cast(bf16x8, vf[s & 1][db]), __builtin_bit_cast(bf16x8, pw[s]), o[db], 0, 0, 0);
;                 FA_SB();
;             }
.LBB0_508:
	ds_read_b128 v[48:51], v149 offset:16416
	ds_read_b128 v[52:55], v149 offset:21024
	ds_read_b128 v[56:59], v149 offset:16448
	ds_read_b128 v[60:63], v149 offset:21056
	v_exp_f32_e32 v132, v132
	v_exp_f32_e32 v133, v133
	v_exp_f32_e32 v130, v130
	v_exp_f32_e32 v131, v131
	v_add_f32_e32 v208, v132, v133
	v_cvt_pk_bf16_f32 v32, v132, v133
	v_exp_f32_e32 v128, v128
	v_add_f32_e32 v208, v130, v208
	v_exp_f32_e32 v129, v129
	v_add_f32_e32 v208, v131, v208
	v_cvt_pk_bf16_f32 v33, v130, v131
	v_exp_f32_e32 v126, v126
	v_add_f32_e32 v208, v128, v208
	v_exp_f32_e32 v127, v127
	v_add_f32_e32 v208, v129, v208
	v_cvt_pk_bf16_f32 v34, v128, v129
	v_exp_f32_e32 v124, v124
	v_add_f32_e32 v208, v126, v208
	v_exp_f32_e32 v125, v125
	v_add_f32_e32 v208, v127, v208
	v_cvt_pk_bf16_f32 v35, v126, v127
	v_exp_f32_e32 v122, v122
	v_add_f32_e32 v208, v124, v208
	s_waitcnt lgkmcnt(4)
	v_mfma_f32_32x32x16_bf16 v[0:15], v[92:95], v[32:35], v[0:15]
	v_exp_f32_e32 v123, v123
	v_add_f32_e32 v208, v125, v208
	v_cvt_pk_bf16_f32 v36, v124, v125
	v_exp_f32_e32 v118, v118
	v_add_f32_e32 v208, v122, v208
	v_mfma_f32_32x32x16_bf16 v[16:31], v[88:91], v[32:35], v[16:31]
	ds_read_b128 v[92:95], v149 offset:16480
	ds_read_b128 v[88:91], v149 offset:21088
	v_exp_f32_e32 v119, v119
	v_add_f32_e32 v208, v123, v208
	v_cvt_pk_bf16_f32 v37, v122, v123
	v_exp_f32_e32 v112, v112
	v_add_f32_e32 v208, v118, v208
	v_exp_f32_e32 v113, v113
	v_add_f32_e32 v208, v119, v208
	v_cvt_pk_bf16_f32 v38, v118, v119
	v_exp_f32_e32 v120, v120
	v_add_f32_e32 v208, v112, v208
	v_exp_f32_e32 v121, v121
	v_add_f32_e32 v208, v113, v208
	v_cvt_pk_bf16_f32 v39, v112, v113
	v_exp_f32_e32 v116, v116
	v_add_f32_e32 v208, v120, v208
	s_waitcnt lgkmcnt(4)
	v_mfma_f32_32x32x16_bf16 v[0:15], v[48:51], v[36:39], v[0:15]
	v_exp_f32_e32 v117, v117
	v_add_f32_e32 v208, v121, v208
	v_cvt_pk_bf16_f32 v40, v120, v121
	v_exp_f32_e32 v114, v114
	v_add_f32_e32 v208, v116, v208
	v_mfma_f32_32x32x16_bf16 v[16:31], v[52:55], v[36:39], v[16:31]
	v_exp_f32_e32 v115, v115
	v_add_f32_e32 v208, v117, v208
	v_cvt_pk_bf16_f32 v41, v116, v117
	v_exp_f32_e32 v110, v110
	v_add_f32_e32 v208, v114, v208
	v_exp_f32_e32 v111, v111
	v_add_f32_e32 v208, v115, v208
	v_cvt_pk_bf16_f32 v42, v114, v115
	v_exp_f32_e32 v108, v108
	v_add_f32_e32 v208, v110, v208
	v_exp_f32_e32 v109, v109
	v_add_f32_e32 v208, v111, v208
	v_cvt_pk_bf16_f32 v43, v110, v111
	v_exp_f32_e32 v106, v106
	v_add_f32_e32 v208, v108, v208
	s_waitcnt lgkmcnt(2)
	v_mfma_f32_32x32x16_bf16 v[0:15], v[56:59], v[40:43], v[0:15]
	v_exp_f32_e32 v107, v107
	v_add_f32_e32 v208, v109, v208
	v_cvt_pk_bf16_f32 v44, v108, v109
	v_exp_f32_e32 v104, v104
	v_add_f32_e32 v208, v106, v208
	v_mfma_f32_32x32x16_bf16 v[16:31], v[60:63], v[40:43], v[16:31]
	v_exp_f32_e32 v105, v105
	v_add_f32_e32 v208, v107, v208
	v_cvt_pk_bf16_f32 v45, v106, v107
	v_exp_f32_e32 v102, v102
	v_add_f32_e32 v208, v104, v208
	v_exp_f32_e32 v103, v103
	v_add_f32_e32 v208, v105, v208
	v_cvt_pk_bf16_f32 v46, v104, v105
	v_add_f32_e32 v208, v102, v208
	v_add_f32_e32 v208, v103, v208
	v_cvt_pk_bf16_f32 v47, v102, v103
	s_nop 1
	s_waitcnt lgkmcnt(0)
	v_mfma_f32_32x32x16_bf16 v[0:15], v[92:95], v[44:47], v[0:15]
	v_mfma_f32_32x32x16_bf16 v[16:31], v[88:91], v[44:47], v[16:31]
	v_add_f32_e32 v137, v137, v208
	s_mov_b64 s[6:7], 0
	s_andn2_b64 vcc, exec, s[4:5]
	s_cbranch_vccnz .LBB0_510

; #define FLAS __attribute__((address_space(3)))
; #define FA_SB() __builtin_amdgcn_sched_barrier(0)
; __device__ __forceinline__ unsigned cvtpk(float lo, float hi) { f32x2_t v = {lo, hi}; bf16x2_t b = __builtin_convertvector(v, bf16x2_t); return __builtin_bit_cast(unsigned, b); }
; template <int MODE> __device__ __forceinline__ void attn_unit(FLAS unsigned char* lds, const Unit u) {
;     ...
;             float ps = 0.f;
; #pragma unroll
;             for (int r = 0; r < 16; ++r) { p0[r] = __builtin_amdgcn_exp2f(p0[r]); p1[r] = __builtin_amdgcn_exp2f(p1[r]); ps += p0[r] + p1[r]; }
;             lsum += ps;
;             u32x4 pw[4];
;             pw[0] = (u32x4){cvtpk(p0[0], p0[1]), cvtpk(p0[2], p0[3]), cvtpk(p0[4], p0[5]), cvtpk(p0[6], p0[7])};
;             pw[1] = (u32x4){cvtpk(p0[8], p0[9]), cvtpk(p0[10], p0[11]), cvtpk(p0[12], p0[13]), cvtpk(p0[14], p0[15])};
;             pw[2] = (u32x4){cvtpk(p1[0], p1[1]), cvtpk(p1[2], p1[3]), cvtpk(p1[4], p1[5]), cvtpk(p1[6], p1[7])};
;             pw[3] = (u32x4){cvtpk(p1[8], p1[9]), cvtpk(p1[10], p1[11]), cvtpk(p1[12], p1[13]), cvtpk(p1[14], p1[15])};
;             FA_SB();
; #pragma unroll
;             for (int s = 0; s < 4; ++s) {
;                 if (s < 3) {
; #pragma unroll
;                     for (int db = 0; db < NDB; ++db) vf[(s + 1) & 1][db] = *(const FLAS u32x4*)(vb + db * 32 * VPITCH + (s + 1) * 32); }
; #pragma unroll
;                 for (int db = 0; db < NDB; ++db) o[db] = __builtin_amdgcn_mfma_f32_32x32x16_bf16(__builtin_bit_cast(bf16x8, vf[s & 1][db]), __builtin_bit_cast(bf16x8, pw[s]), o[db], 0, 0, 0);
;                 FA_SB();
;             }
.LBB0_538:
	ds_read_b128 v[48:51], v149 offset:16416
	ds_read_b128 v[52:55], v149 offset:21024
	ds_read_b128 v[56:59], v149 offset:16448
	ds_read_b128 v[60:63], v149 offset:21056
	v_exp_f32_e32 v132, v132
	v_exp_f32_e32 v133, v133
	v_exp_f32_e32 v130, v130
	v_exp_f32_e32 v131, v131
	v_add_f32_e32 v208, v132, v133
	v_cvt_pk_bf16_f32 v32, v132, v133
	v_exp_f32_e32 v128, v128
	v_add_f32_e32 v208, v130, v208
	v_exp_f32_e32 v129, v129
	v_add_f32_e32 v208, v131, v208
	v_cvt_pk_bf16_f32 v33, v130, v131
	v_exp_f32_e32 v126, v126
	v_add_f32_e32 v208, v128, v208
	v_exp_f32_e32 v127, v127
	v_add_f32_e32 v208, v129, v208
	v_cvt_pk_bf16_f32 v34, v128, v129
	v_exp_f32_e32 v124, v124
	v_add_f32_e32 v208, v126, v208
	v_exp_f32_e32 v125, v125
	v_add_f32_e32 v208, v127, v208
	v_cvt_pk_bf16_f32 v35, v126, v127
	v_exp_f32_e32 v122, v122
	v_add_f32_e32 v208, v124, v208
	s_waitcnt lgkmcnt(4)
	v_mfma_f32_32x32x16_bf16 v[0:15], v[92:95], v[32:35], v[0:15]
	v_exp_f32_e32 v123, v123
	v_add_f32_e32 v208, v125, v208
	v_cvt_pk_bf16_f32 v36, v124, v125
	v_exp_f32_e32 v118, v118
	v_add_f32_e32 v208, v122, v208
	v_mfma_f32_32x32x16_bf16 v[16:31], v[88:91], v[32:35], v[16:31]
	ds_read_b128 v[92:95], v149 offset:16480
	ds_read_b128 v[88:91], v149 offset:21088
	v_exp_f32_e32 v119, v119
	v_add_f32_e32 v208, v123, v208
	v_cvt_pk_bf16_f32 v37, v122, v123
	v_exp_f32_e32 v112, v112
	v_add_f32_e32 v208, v118, v208
	v_exp_f32_e32 v113, v113
	v_add_f32_e32 v208, v119, v208
	v_cvt_pk_bf16_f32 v38, v118, v119
	v_exp_f32_e32 v120, v120
	v_add_f32_e32 v208, v112, v208
	v_exp_f32_e32 v121, v121
	v_add_f32_e32 v208, v113, v208
	v_cvt_pk_bf16_f32 v39, v112, v113
	v_exp_f32_e32 v116, v116
	v_add_f32_e32 v208, v120, v208
	s_waitcnt lgkmcnt(4)
	v_mfma_f32_32x32x16_bf16 v[0:15], v[48:51], v[36:39], v[0:15]
	v_exp_f32_e32 v117, v117
	v_add_f32_e32 v208, v121, v208
	v_cvt_pk_bf16_f32 v40, v120, v121
	v_exp_f32_e32 v114, v114
	v_add_f32_e32 v208, v116, v208
	v_mfma_f32_32x32x16_bf16 v[16:31], v[52:55], v[36:39], v[16:31]
	v_exp_f32_e32 v115, v115
	v_add_f32_e32 v208, v117, v208
	v_cvt_pk_bf16_f32 v41, v116, v117
	v_exp_f32_e32 v110, v110
	v_add_f32_e32 v208, v114, v208
	v_exp_f32_e32 v111, v111
	v_add_f32_e32 v208, v115, v208
	v_cvt_pk_bf16_f32 v42, v114, v115
	v_exp_f32_e32 v108, v108
	v_add_f32_e32 v208, v110, v208
	v_exp_f32_e32 v109, v109
	v_add_f32_e32 v208, v111, v208
	v_cvt_pk_bf16_f32 v43, v110, v111
	v_exp_f32_e32 v106, v106
	v_add_f32_e32 v208, v108, v208
	s_waitcnt lgkmcnt(2)
	v_mfma_f32_32x32x16_bf16 v[0:15], v[56:59], v[40:43], v[0:15]
	v_exp_f32_e32 v107, v107
	v_add_f32_e32 v208, v109, v208
	v_cvt_pk_bf16_f32 v44, v108, v109
	v_exp_f32_e32 v104, v104
	v_add_f32_e32 v208, v106, v208
	v_mfma_f32_32x32x16_bf16 v[16:31], v[60:63], v[40:43], v[16:31]
	v_exp_f32_e32 v105, v105
	v_add_f32_e32 v208, v107, v208
	v_cvt_pk_bf16_f32 v45, v106, v107
	v_exp_f32_e32 v102, v102
	v_add_f32_e32 v208, v104, v208
	v_exp_f32_e32 v103, v103
	v_add_f32_e32 v208, v105, v208
	v_cvt_pk_bf16_f32 v46, v104, v105
	v_add_f32_e32 v208, v102, v208
	v_add_f32_e32 v208, v103, v208
	v_cvt_pk_bf16_f32 v47, v102, v103
	s_nop 1
	s_waitcnt lgkmcnt(0)
	v_mfma_f32_32x32x16_bf16 v[0:15], v[92:95], v[44:47], v[0:15]
	v_mfma_f32_32x32x16_bf16 v[16:31], v[88:91], v[44:47], v[16:31]
	v_add_f32_e32 v146, v146, v208
	s_mov_b64 s[22:23], 0
